# FFN-out exchange: dead address set-up of the former pass-2 residual re-loads and the barrier ahead of the slot polling removed
# baseline (speedup 1.0000x reference)
.LBB0_737:
	s_or_b64 exec, exec, s[48:49]
	s_waitcnt lgkmcnt(0)
	s_and_saveexec_b64 s[48:49], s[34:35]
	s_cbranch_execz .LBB0_739
	s_ashr_i32 s47, s46, 31
	s_lshl_b64 s[36:37], s[46:47], 12
	v_lshl_add_u64 v[136:137], v[172:173], 0, s[36:37]
	s_mov_b32 s33, 0
